# FL2: XCD leaders arrive with one no-return add on a single counter and all workgroups poll it (drops the returning cross-XCD add and the generation relay), on top of v070
# speedup vs baseline: 1.0031x; 1.0020x over previous
.Lfl_poll:
	s_waitcnt lgkmcnt(0)
	v_readfirstlane_b32 s1, v2
	v_readlane_b32 s0, v243, 19
	s_lshl_b32 s28, 2, s0
	s_add_i32 s28, s28, -1
	s_and_b32 s28, s28, 0x1605b
	s_bcnt1_i32_b32 s0, s28
	s_mul_i32 s0, s0, s1
	s_add_u32 s28, s96, 0xeb14700
	s_addc_u32 s29, s97, 0
.Lfl_wait:
	global_load_dword v4, v0, s[28:29] sc1
	s_waitcnt vmcnt(0)
	v_readfirstlane_b32 s1, v4
	s_cmp_ge_u32 s1, s0
	s_cbranch_scc1 .Lfl_done
	s_sleep 1
	s_branch .Lfl_wait
.Lfl_done:
	buffer_inv sc1
	s_waitcnt vmcnt(0)
	s_branch .LBB0_7

.LBB0_423:
	s_or_b64 exec, exec, s[28:29]
	v_cvt_f32_u32_e32 v5, v3
	s_waitcnt vmcnt(0)
	v_readfirstlane_b32 s0, v4
	v_sub_u32_e32 v4, 0, v3
	v_rcp_iflag_f32_e32 v5, v5
	v_add_u32_e32 v6, s0, v1
	v_mul_f32_e32 v5, 0x4f7ffffe, v5
	v_cvt_u32_f32_e32 v5, v5
	v_mul_lo_u32 v1, v4, v5
	v_mul_hi_u32 v1, v5, v1
	v_add_u32_e32 v1, v5, v1
	v_mul_hi_u32 v1, v6, v1
	v_mul_lo_u32 v4, v1, v3
	v_sub_u32_e32 v4, v6, v4
	v_add_u32_e32 v5, 1, v1
	v_cmp_ge_u32_e32 vcc, v4, v3
	s_nop 1
	v_cndmask_b32_e32 v1, v1, v5, vcc
	v_sub_u32_e32 v5, v4, v3
	v_cndmask_b32_e32 v4, v4, v5, vcc
	v_add_u32_e32 v5, 1, v1
	v_cmp_ge_u32_e32 vcc, v4, v3
	v_add_u32_e32 v4, 1, v6
	s_nop 0
	v_cndmask_b32_e32 v1, v1, v5, vcc
	v_mul_lo_u32 v5, v3, v1
	v_add_u32_e32 v3, v5, v3
	v_cmp_ne_u32_e32 vcc, v4, v3
	s_and_saveexec_b64 s[0:1], vcc
	s_xor_b64 s[28:29], exec, s[0:1]
	s_cbranch_execz .LBB0_437
	s_cmpk_eq_u32 s98, 0x100
	s_cbranch_scc1 .Lfl_poll
	v_readlane_b32 s0, v248, 44
	v_readlane_b32 s1, v248, 45
	s_waitcnt lgkmcnt(0)
	s_nop 3
	global_load_dword v2, v0, s[0:1] sc1
	s_waitcnt vmcnt(0)
	v_cmp_eq_u32_e32 vcc, v2, v1
	s_and_saveexec_b64 s[34:35], vcc
	s_cbranch_execz .LBB0_436
	s_mov_b32 s0, 1
	s_mov_b64 s[38:39], 0
	s_branch .LBB0_427

.LBB0_437:
	s_andn2_saveexec_b64 s[0:1], s[28:29]
	s_cbranch_execz .LBB0_7
	s_mov_b64 s[28:29], exec
	buffer_wbl2 sc1
	s_waitcnt lgkmcnt(0)
	s_waitcnt vmcnt(0)
	s_cmpk_lg_u32 s98, 0x100
	s_cbranch_scc1 .Lfl_orig
	s_add_u32 s0, s96, 0xeb14700
	s_addc_u32 s1, s97, 0
	v_mov_b32_e32 v1, 1
	global_atomic_add v0, v1, s[0:1]
	s_branch .Lfl_poll
.Lfl_orig:
	v_mbcnt_lo_u32_b32 v1, s28, 0
	v_mbcnt_hi_u32_b32 v1, s29, v1
	v_cmp_eq_u32_e32 vcc, 0, v1
	s_and_saveexec_b64 s[34:35], vcc
	s_cbranch_execz .LBB0_440
	s_bcnt1_i32_b64 s0, s[28:29]
	v_mov_b32_e32 v3, s0
	v_readlane_b32 s0, v248, 42
	v_readlane_b32 s1, v248, 43
	s_nop 4
	global_atomic_add v3, v0, v3, s[0:1] sc0
